# v65 + P4 mlstm_out C_k^T loads issued with the Q/K burst + P5 decode-row LayerNorm gamma/beta loads all in flight (3 load+drain rounds removed on vcu<16)
# baseline (speedup 1.0000x reference)
.LBB0_1158:
	v_lshl_add_u64 v[26:27], s[4:5], 0, v[18:19]
	global_load_dwordx4 v[22:25], v[26:27], off offset:-2048
	global_load_dwordx4 v[10:13], v[26:27], off offset:-1024
	global_load_dwordx4 v[6:9], v[26:27], off
	global_load_dwordx4 v[2:5], v[26:27], off offset:1024
	s_nop 0
	global_load_dwordx4 v[26:29], v[14:15], off
	global_load_dwordx4 v[30:33], v[16:17], off
	global_load_dwordx4 v[44:47], v[14:15], off offset:1024
	global_load_dwordx4 v[48:51], v[16:17], off offset:1024
	global_load_dwordx4 v[52:55], v[14:15], off offset:2048
	global_load_dwordx4 v[56:59], v[16:17], off offset:2048
	global_load_dwordx4 v[60:63], v[14:15], off offset:3072
	global_load_dwordx4 v[64:67], v[16:17], off offset:3072
	v_lshl_add_u64 v[34:35], s[8:9], 0, v[18:19]
	s_add_i32 s10, s10, s2
	v_lshl_add_u64 v[18:19], v[18:19], 0, s[6:7]
	s_cmpk_lt_i32 s10, 0x80
	s_waitcnt vmcnt(11)
	v_add_f32_e32 v21, v22, v23
	v_add_f32_e32 v36, v24, v25
	s_waitcnt vmcnt(10)
	v_add_f32_e32 v37, v10, v11
	v_add_f32_e32 v38, v12, v13
	v_add_f32_e32 v21, v21, v36
	s_waitcnt vmcnt(9)
	v_add_f32_e32 v39, v6, v7
	v_add_f32_e32 v40, v8, v9
	v_add_f32_e32 v36, v37, v38
	v_add_f32_e32 v21, 0, v21
	s_waitcnt vmcnt(8)
	v_add_f32_e32 v41, v2, v3
	v_add_f32_e32 v42, v4, v5
	v_add_f32_e32 v37, v39, v40
	v_add_f32_e32 v21, v21, v36
	v_add_f32_e32 v38, v41, v42
	v_add_f32_e32 v21, v21, v37
	v_add_f32_e32 v21, v21, v38
	s_nop 1
	v_add_f32_dpp v21, v21, v21 quad_perm:[1,0,3,2] row_mask:0xf bank_mask:0xf bound_ctrl:1
	s_nop 1
	v_add_f32_dpp v21, v21, v21 quad_perm:[2,3,0,1] row_mask:0xf bank_mask:0xf bound_ctrl:1
	s_nop 1
	v_add_f32_dpp v21, v21, v21 row_ror:4 row_mask:0xf bank_mask:0xf bound_ctrl:1
	s_nop 1
	v_add_f32_dpp v21, v21, v21 row_ror:8 row_mask:0xf bank_mask:0xf bound_ctrl:1
	v_mov_b32_e32 v36, v21
	s_nop 1
	v_permlane16_swap_b32_e32 v21, v36
	v_add_f32_e32 v21, v21, v36
	v_mov_b32_e32 v36, v21
	s_nop 1
	v_permlane32_swap_b32_e32 v21, v36
	v_add_f32_e32 v21, v21, v36
	v_fmamk_f32 v25, v21, 0xba800000, v25
	v_fmac_f32_e32 v23, 0xba800000, v21
	v_fmamk_f32 v13, v21, 0xba800000, v13
	v_fmac_f32_e32 v11, 0xba800000, v21
	v_fmamk_f32 v24, v21, 0xba800000, v24
	v_fmamk_f32 v22, v21, 0xba800000, v22
	v_fmamk_f32 v12, v21, 0xba800000, v12
	v_fmamk_f32 v10, v21, 0xba800000, v10
	v_fmamk_f32 v36, v21, 0xba800000, v8
	v_fmamk_f32 v37, v21, 0xba800000, v9
	v_fmac_f32_e32 v7, 0xba800000, v21
	v_fmamk_f32 v38, v21, 0xba800000, v4
	v_fmamk_f32 v39, v21, 0xba800000, v5
	v_mul_f32_e32 v4, v23, v23
	v_mul_f32_e32 v5, v25, v25
	v_mul_f32_e32 v8, v11, v11
	v_mul_f32_e32 v9, v13, v13
	v_fmamk_f32 v6, v21, 0xba800000, v6
	v_fmamk_f32 v2, v21, 0xba800000, v2
	v_fmac_f32_e32 v3, 0xba800000, v21
	v_mul_f32_e32 v21, v7, v7
	v_mul_f32_e32 v40, v37, v37
	v_fmac_f32_e32 v4, v22, v22
	v_fmac_f32_e32 v5, v24, v24
	v_fmac_f32_e32 v8, v10, v10
	v_fmac_f32_e32 v9, v12, v12
	v_mul_f32_e32 v41, v3, v3
	v_mul_f32_e32 v42, v39, v39
	v_fmac_f32_e32 v21, v6, v6
	v_fmac_f32_e32 v40, v36, v36
	v_add_f32_e32 v4, v4, v5
	v_add_f32_e32 v5, v8, v9
	v_fmac_f32_e32 v41, v2, v2
	v_fmac_f32_e32 v42, v38, v38
	v_add_f32_e32 v8, v21, v40
	v_add_f32_e32 v4, v4, v5
	v_add_f32_e32 v9, v41, v42
	v_add_f32_e32 v4, v8, v4
	v_add_f32_e32 v4, v9, v4
	s_nop 1
	v_add_f32_dpp v4, v4, v4 quad_perm:[1,0,3,2] row_mask:0xf bank_mask:0xf bound_ctrl:1
	s_nop 1
	v_add_f32_dpp v4, v4, v4 quad_perm:[2,3,0,1] row_mask:0xf bank_mask:0xf bound_ctrl:1
	s_nop 1
	v_add_f32_dpp v4, v4, v4 row_ror:4 row_mask:0xf bank_mask:0xf bound_ctrl:1
	s_nop 1
	v_add_f32_dpp v4, v4, v4 row_ror:8 row_mask:0xf bank_mask:0xf bound_ctrl:1
	v_mov_b32_e32 v5, v4
	s_nop 1
	v_permlane16_swap_b32_e32 v4, v5
	v_add_f32_e32 v4, v4, v5
	v_mov_b32_e32 v5, v4
	s_nop 1
	v_permlane32_swap_b32_e32 v4, v5
	v_add_f32_e32 v4, v4, v5
	v_fmamk_f32 v4, v4, 0x3a800000, v1
	v_mul_f32_e32 v5, 0x4f800000, v4
	v_cmp_gt_f32_e32 vcc, s3, v4
	s_nop 1
	v_cndmask_b32_e32 v4, v4, v5, vcc
	v_sqrt_f32_e32 v5, v4
	s_nop 0
	v_add_u32_e32 v8, -1, v5
	v_add_u32_e32 v9, 1, v5
	v_fma_f32 v21, -v8, v5, v4
	v_fma_f32 v40, -v9, v5, v4
	v_cmp_ge_f32_e64 s[0:1], 0, v21
	s_nop 1
	v_cndmask_b32_e64 v5, v5, v8, s[0:1]
	v_cmp_lt_f32_e64 s[0:1], 0, v40
	s_nop 1
	v_cndmask_b32_e64 v5, v5, v9, s[0:1]
	v_mul_f32_e32 v8, 0x37800000, v5
	v_cndmask_b32_e32 v5, v5, v8, vcc
	v_cmp_class_f32_e32 vcc, v4, v20
	s_nop 1
	v_cndmask_b32_e32 v4, v5, v4, vcc
	v_div_scale_f32 v5, s[0:1], v4, v4, 1.0
	v_rcp_f32_e32 v9, v5
	v_div_scale_f32 v8, vcc, 1.0, v4, 1.0
	v_fma_f32 v21, -v5, v9, 1.0
	v_fmac_f32_e32 v9, v21, v9
	v_mul_f32_e32 v21, v8, v9
	v_fma_f32 v40, -v5, v21, v8
	v_fmac_f32_e32 v21, v40, v9
	v_fma_f32 v5, -v5, v21, v8
	v_div_fmas_f32 v5, v5, v9, v21
	v_div_fixup_f32 v40, v5, v4, 1.0
	v_pk_mul_f32 v[4:5], v[22:23], v[40:41] op_sel_hi:[1,0]
	v_pk_mul_f32 v[8:9], v[24:25], v[40:41] op_sel_hi:[1,0]
	s_waitcnt vmcnt(0)
	v_pk_fma_f32 v[22:23], v[26:27], v[4:5], v[30:31]
	v_pk_fma_f32 v[24:25], v[28:29], v[8:9], v[32:33]
	global_store_dwordx4 v[34:35], v[22:25], off offset:-2048
	s_nop 0
	v_pk_mul_f32 v[4:5], v[12:13], v[40:41] op_sel_hi:[1,0]
	v_pk_mul_f32 v[8:9], v[10:11], v[40:41] op_sel_hi:[1,0]
	v_pk_mul_f32 v[12:13], v[36:37], v[40:41] op_sel_hi:[1,0]
	v_pk_mul_f32 v[2:3], v[2:3], v[40:41] op_sel_hi:[1,0]
	v_pk_fma_f32 v[8:9], v[44:45], v[8:9], v[48:49]
	v_pk_fma_f32 v[10:11], v[46:47], v[4:5], v[50:51]
	global_store_dwordx4 v[34:35], v[8:11], off offset:-1024
	s_nop 1
	s_nop 0
	v_pk_mul_f32 v[4:5], v[6:7], v[40:41] op_sel_hi:[1,0]
	v_pk_fma_f32 v[6:7], v[54:55], v[12:13], v[58:59]
	v_pk_fma_f32 v[4:5], v[52:53], v[4:5], v[56:57]
	global_store_dwordx4 v[34:35], v[4:7], off
	s_nop 1
	s_nop 0
	v_pk_mul_f32 v[12:13], v[38:39], v[40:41] op_sel_hi:[1,0]
	v_pk_fma_f32 v[2:3], v[2:3], v[60:61], v[64:65]
	v_pk_fma_f32 v[4:5], v[12:13], v[62:63], v[66:67]
	global_store_dwordx4 v[34:35], v[2:5], off offset:1024
	s_cbranch_scc1 .LBB0_1158
